# P4 epilogue batched loads + GLA pass C stage A1 pipelined over 4 tiles, next-chunk alr prefetch
# speedup vs baseline: 1.0063x; 1.0063x over previous
; #define LAS __attribute__((address_space(3)))
; __device__ __forceinline__ void unpack8(const u32x4 w, float (&f)[8]) { f[0] = bflo(w.x); f[1] = bfhi(w.x); f[2] = bflo(w.y); f[3] = bfhi(w.y); f[4] = bflo(w.z); f[5] = bfhi(w.z); f[6] = bflo(w.w); f[7] = bfhi(w.w); }
; #define MFMA16(a, b, c) __builtin_amdgcn_mfma_f32_16x16x32_bf16((a), (b), (c), 0, 0, 0)
; __device__ __forceinline__ u32x4 pack8v(const float (&f)[8]) { u32x4 w; w.x = pk2v(f[0], f[1]); w.y = pk2v(f[2], f[3]); w.z = pk2v(f[4], f[5]); w.w = pk2v(f[6], f[7]); return w; }
; #define GLA_LOAD_QKV(T0) do { _Pragma("unroll") for (int i_ = 0; i_ < 2; ++i_) { const int oc_ = lo + 8 * i_; \
;             kw[i_] = *(const u32x4*)(QK + ((T0) + lt) * 1024 + 512 + h * 128 + oc_ * 8); } \
;         _Pragma("unroll") for (int i_ = 0; i_ < 4; ++i_) { const int oc_ = lo + 8 * i_; vw[i_] = *(const u32x4*)(GV + ((T0) + lt) * 1024 + h * 256 + oc_ * 8); } } while (0)
; template <bool FULL> ...
;     ...
;     for (int c = 0; c < GLA_SEGC; ++c) {
;         const size_t tok0 = tokb + (size_t)c * 64;
;         GLA_LOAD_QKV(tok0);
;         if (FULL) {
; #pragma unroll
;             for (int i = 0; i < 2; ++i) qw[i] = *(const u32x4*)(QK + (tok0 + lt) * 1024 + h * 128 + (lo + 8 * i) * 8); }
;         {
;             float carry = 0.f;
; #pragma unroll
;             for (int tt = 0; tt < 4; ++tt) {
;                 const LAS f32x4* ar = (const LAS f32x4*)(ALRS + (tt * 16 + fr) * 16 + (fq & 1) * 8); const f32x4 x0 = ar[0], x1 = ar[1];
;                 float x[8] = {x0.x, x0.y, x0.z, x0.w, x1.x, x1.y, x1.z, x1.w}, xh[8];
;                 unpack8(pack8v(x), xh);
;                 if (fq >= 2) {
; #pragma unroll
;                     for (int e = 0; e < 8; ++e) x[e] -= xh[e];
;                 }
;                 const bf16x8 af = __builtin_bit_cast(bf16x8, pack8v(x));
;                 const f32x4 z4 = MFMA16(af, w2f, ((f32x4){0.f, 0.f, 0.f, 0.f}));
;                 float v[4];
; #pragma unroll
;                 for (int i = 0; i < 4; ++i) { const float z = z4[i] + bz;
;                     v[i] = (fminf(z, 0.f) - 0.6931471805599453f * __builtin_amdgcn_logf(1.0f + __builtin_amdgcn_exp2f(-1.4426950408889634f * fabsf(z)))) * (1.0f / 16.0f); }
.LBB0_446:
	s_cmp_lg_u32 s64, 0xe0000
	s_cselect_b64 s[28:29], -1, 0
	s_and_b64 s[28:29], vcc, s[28:29]
	s_and_saveexec_b64 s[66:67], s[28:29]
	s_cbranch_execz .Lgla_c_noalr
	global_load_dwordx4 v[242:245], v[150:151], off
.Lgla_c_noalr:
	s_or_b64 exec, exec, s[66:67]
	v_lshl_add_u64 v[88:89], v[168:169], 0, s[64:65]
	v_lshl_add_u64 v[72:73], v[170:171], 0, s[64:65]
	global_load_dwordx4 v[100:103], v[88:89], off
	global_load_dwordx4 v[92:95], v[88:89], off offset:128
	global_load_dwordx4 v[84:87], v[72:73], off offset:-256
	global_load_dwordx4 v[80:83], v[72:73], off offset:-128
	global_load_dwordx4 v[76:79], v[72:73], off
	s_nop 0
	global_load_dwordx4 v[72:75], v[72:73], off offset:128
	s_nop 0
	global_load_dwordx4 v[96:99], v[88:89], off offset:-1024
	s_nop 0
	global_load_dwordx4 v[88:91], v[88:89], off offset:-896
	ds_read_b128 v[104:107], v225
	ds_read_b128 v[108:111], v225 offset:16
	ds_read_b128 v[112:115], v227
	ds_read_b128 v[116:119], v227 offset:16
	s_waitcnt lgkmcnt(2)
	s_and_saveexec_b64 s[66:67], s[0:1]
	v_cvt_pk_bf16_f32 v136, v104, v105
	v_cvt_pk_bf16_f32 v137, v106, v107
	v_and_b32_e32 v138, 0xffff0000, v136
	v_lshlrev_b32_e32 v136, 16, v136
	v_and_b32_e32 v139, 0xffff0000, v137
	v_lshlrev_b32_e32 v137, 16, v137
	v_sub_f32_e32 v104, v104, v136
	v_sub_f32_e32 v105, v105, v138
	v_sub_f32_e32 v106, v106, v137
	v_sub_f32_e32 v107, v107, v139
	v_cvt_pk_bf16_f32 v136, v108, v109
	v_cvt_pk_bf16_f32 v137, v110, v111
	v_and_b32_e32 v138, 0xffff0000, v136
	v_lshlrev_b32_e32 v136, 16, v136
	v_and_b32_e32 v139, 0xffff0000, v137
	v_lshlrev_b32_e32 v137, 16, v137
	v_sub_f32_e32 v108, v108, v136
	v_sub_f32_e32 v109, v109, v138
	v_sub_f32_e32 v110, v110, v137
	v_sub_f32_e32 v111, v111, v139
	s_or_b64 exec, exec, s[66:67]
	v_cvt_pk_bf16_f32 v104, v104, v105
	v_cvt_pk_bf16_f32 v105, v106, v107
	v_cvt_pk_bf16_f32 v106, v108, v109
	v_cvt_pk_bf16_f32 v107, v110, v111
	s_nop 1
	v_mfma_f32_16x16x32_bf16 v[120:123], v[104:107], v[68:71], 0
	ds_read_b128 v[104:107], v228
	ds_read_b128 v[108:111], v228 offset:16
	s_waitcnt lgkmcnt(2)
	s_and_saveexec_b64 s[66:67], s[0:1]
	v_cvt_pk_bf16_f32 v136, v112, v113
	v_cvt_pk_bf16_f32 v137, v114, v115
	v_and_b32_e32 v138, 0xffff0000, v136
	v_lshlrev_b32_e32 v136, 16, v136
	v_and_b32_e32 v139, 0xffff0000, v137
	v_lshlrev_b32_e32 v137, 16, v137
	v_sub_f32_e32 v112, v112, v136
	v_sub_f32_e32 v113, v113, v138
	v_sub_f32_e32 v114, v114, v137
	v_sub_f32_e32 v115, v115, v139
	v_cvt_pk_bf16_f32 v136, v116, v117
	v_cvt_pk_bf16_f32 v137, v118, v119
	v_and_b32_e32 v138, 0xffff0000, v136
	v_lshlrev_b32_e32 v136, 16, v136
	v_and_b32_e32 v139, 0xffff0000, v137
	v_lshlrev_b32_e32 v137, 16, v137
	v_sub_f32_e32 v116, v116, v136
	v_sub_f32_e32 v117, v117, v138
	v_sub_f32_e32 v118, v118, v137
	v_sub_f32_e32 v119, v119, v139
	s_or_b64 exec, exec, s[66:67]
	v_cvt_pk_bf16_f32 v112, v112, v113
	v_cvt_pk_bf16_f32 v113, v114, v115
	v_cvt_pk_bf16_f32 v114, v116, v117
	v_cvt_pk_bf16_f32 v115, v118, v119
	s_nop 1
	v_mfma_f32_16x16x32_bf16 v[124:127], v[112:115], v[68:71], 0
	ds_read_b128 v[112:115], v229
	ds_read_b128 v[116:119], v229 offset:16
	s_waitcnt lgkmcnt(2)
	s_and_saveexec_b64 s[66:67], s[0:1]
	v_cvt_pk_bf16_f32 v136, v104, v105
	v_cvt_pk_bf16_f32 v137, v106, v107
	v_and_b32_e32 v138, 0xffff0000, v136
	v_lshlrev_b32_e32 v136, 16, v136
	v_and_b32_e32 v139, 0xffff0000, v137
	v_lshlrev_b32_e32 v137, 16, v137
	v_sub_f32_e32 v104, v104, v136
	v_sub_f32_e32 v105, v105, v138
	v_sub_f32_e32 v106, v106, v137
	v_sub_f32_e32 v107, v107, v139
	v_cvt_pk_bf16_f32 v136, v108, v109
	v_cvt_pk_bf16_f32 v137, v110, v111
	v_and_b32_e32 v138, 0xffff0000, v136
	v_lshlrev_b32_e32 v136, 16, v136
	v_and_b32_e32 v139, 0xffff0000, v137
	v_lshlrev_b32_e32 v137, 16, v137
	v_sub_f32_e32 v108, v108, v136
	v_sub_f32_e32 v109, v109, v138
	v_sub_f32_e32 v110, v110, v137
	v_sub_f32_e32 v111, v111, v139
	s_or_b64 exec, exec, s[66:67]
	v_cvt_pk_bf16_f32 v104, v104, v105
	v_cvt_pk_bf16_f32 v105, v106, v107
	v_cvt_pk_bf16_f32 v106, v108, v109
	v_cvt_pk_bf16_f32 v107, v110, v111
	s_nop 1
	v_mfma_f32_16x16x32_bf16 v[128:131], v[104:107], v[68:71], 0
	s_waitcnt lgkmcnt(0)
	s_and_saveexec_b64 s[66:67], s[0:1]
	v_cvt_pk_bf16_f32 v136, v112, v113
	v_cvt_pk_bf16_f32 v137, v114, v115
	v_and_b32_e32 v138, 0xffff0000, v136
	v_lshlrev_b32_e32 v136, 16, v136
	v_and_b32_e32 v139, 0xffff0000, v137
	v_lshlrev_b32_e32 v137, 16, v137
	v_sub_f32_e32 v112, v112, v136
	v_sub_f32_e32 v113, v113, v138
	v_sub_f32_e32 v114, v114, v137
	v_sub_f32_e32 v115, v115, v139
	v_cvt_pk_bf16_f32 v136, v116, v117
	v_cvt_pk_bf16_f32 v137, v118, v119
	v_and_b32_e32 v138, 0xffff0000, v136
	v_lshlrev_b32_e32 v136, 16, v136
	v_and_b32_e32 v139, 0xffff0000, v137
	v_lshlrev_b32_e32 v137, 16, v137
	v_sub_f32_e32 v116, v116, v136
	v_sub_f32_e32 v117, v117, v138
	v_sub_f32_e32 v118, v118, v137
	v_sub_f32_e32 v119, v119, v139
	s_or_b64 exec, exec, s[66:67]
	v_cvt_pk_bf16_f32 v112, v112, v113
	v_cvt_pk_bf16_f32 v113, v114, v115
	v_cvt_pk_bf16_f32 v114, v116, v117
	v_cvt_pk_bf16_f32 v115, v118, v119
	s_nop 1
	v_mfma_f32_16x16x32_bf16 v[132:135], v[112:115], v[68:71], 0
	s_nop 3
	v_add_f32_e32 v120, v172, v120
	v_add_f32_e32 v121, v172, v121
	v_add_f32_e32 v122, v172, v122
	v_add_f32_e32 v123, v172, v123
	v_add_f32_e32 v124, v172, v124
	v_add_f32_e32 v125, v172, v125
	v_add_f32_e32 v126, v172, v126
	v_add_f32_e32 v127, v172, v127
	v_add_f32_e32 v128, v172, v128
	v_add_f32_e32 v129, v172, v129
	v_add_f32_e32 v130, v172, v130
	v_add_f32_e32 v131, v172, v131
	v_add_f32_e32 v132, v172, v132
	v_add_f32_e32 v133, v172, v133
	v_add_f32_e32 v134, v172, v134
	v_add_f32_e32 v135, v172, v135
	v_mul_f32_e64 v104, |v120|, s91
; #define LAS __attribute__((address_space(3)))
; template <bool FULL> ...
;     ...
;                 for (int i = 0; i < 4; ++i) { const float z = z4[i] + bz;
;                     v[i] = (fminf(z, 0.f) - 0.6931471805599453f * __builtin_amdgcn_logf(1.0f + __builtin_amdgcn_exp2f(-1.4426950408889634f * fabsf(z)))) * (1.0f / 16.0f); }
;                 v[1] += v[0]; v[2] += v[1]; v[3] += v[2];
;                 const float tot4 = v[3];
;                 const float p1 = __shfl_up(tot4, 16); float sc = tot4 + (fq >= 1 ? p1 : 0.f);
;                 const float p2 = __shfl_up(sc, 32); sc += (fq >= 2 ? p2 : 0.f);
;                 const float base = carry + (sc - tot4);
; #pragma unroll
;                 for (int i = 0; i < 4; ++i) CUM[(tt * 16 + 4 * fq + i) * 132 + dkc] = v[i] + base;
;                 carry += __shfl(sc, 48 + fr);
;             }
;             if (fq == 0) DEC[dkc] = __builtin_amdgcn_exp2f(1.4426950408889634f * carry);
;             segtot += carry;
;         }
;         __syncthreads();
;         if (c + 1 < GLA_SEGC && tid < 256) *(LAS f32x4*)(ALRS + tid * 4) = *(const f32x4*)(ALR + (tok0 + 64) * 16 + tid * 4);
	v_mul_f32_e64 v105, |v121|, s91
	v_mul_f32_e64 v106, |v122|, s91
	v_mul_f32_e64 v107, |v123|, s91
	v_mul_f32_e64 v108, |v124|, s91
	v_mul_f32_e64 v109, |v125|, s91
	v_mul_f32_e64 v110, |v126|, s91
	v_mul_f32_e64 v111, |v127|, s91
	v_mul_f32_e64 v112, |v128|, s91
	v_mul_f32_e64 v113, |v129|, s91
	v_mul_f32_e64 v114, |v130|, s91
	v_mul_f32_e64 v115, |v131|, s91
	v_mul_f32_e64 v116, |v132|, s91
	v_mul_f32_e64 v117, |v133|, s91
	v_mul_f32_e64 v118, |v134|, s91
	v_mul_f32_e64 v119, |v135|, s91
	v_exp_f32_e32 v104, v104
	v_exp_f32_e32 v105, v105
	v_exp_f32_e32 v106, v106
	v_exp_f32_e32 v107, v107
	v_exp_f32_e32 v108, v108
	v_exp_f32_e32 v109, v109
	v_exp_f32_e32 v110, v110
	v_exp_f32_e32 v111, v111
	v_exp_f32_e32 v112, v112
	v_exp_f32_e32 v113, v113
	v_exp_f32_e32 v114, v114
	v_exp_f32_e32 v115, v115
	v_exp_f32_e32 v116, v116
	v_exp_f32_e32 v117, v117
	v_exp_f32_e32 v118, v118
	v_exp_f32_e32 v119, v119
	v_min_f32_e32 v120, 0, v120
	v_min_f32_e32 v121, 0, v121
	v_min_f32_e32 v122, 0, v122
	v_min_f32_e32 v123, 0, v123
	v_min_f32_e32 v124, 0, v124
	v_min_f32_e32 v125, 0, v125
	v_min_f32_e32 v126, 0, v126
	v_min_f32_e32 v127, 0, v127
	v_min_f32_e32 v128, 0, v128
	v_min_f32_e32 v129, 0, v129
	v_min_f32_e32 v130, 0, v130
	v_min_f32_e32 v131, 0, v131
	v_min_f32_e32 v132, 0, v132
	v_min_f32_e32 v133, 0, v133
	v_min_f32_e32 v134, 0, v134
	v_min_f32_e32 v135, 0, v135
	v_add_f32_e32 v104, 1.0, v104
	v_add_f32_e32 v105, 1.0, v105
	v_add_f32_e32 v106, 1.0, v106
	v_add_f32_e32 v107, 1.0, v107
	v_add_f32_e32 v108, 1.0, v108
	v_add_f32_e32 v109, 1.0, v109
	v_add_f32_e32 v110, 1.0, v110
	v_add_f32_e32 v111, 1.0, v111
	v_add_f32_e32 v112, 1.0, v112
	v_add_f32_e32 v113, 1.0, v113
	v_add_f32_e32 v114, 1.0, v114
	v_add_f32_e32 v115, 1.0, v115
	v_add_f32_e32 v116, 1.0, v116
	v_add_f32_e32 v117, 1.0, v117
	v_add_f32_e32 v118, 1.0, v118
	v_add_f32_e32 v119, 1.0, v119
	v_log_f32_e32 v104, v104
	v_log_f32_e32 v105, v105
	v_log_f32_e32 v106, v106
	v_log_f32_e32 v107, v107
	v_log_f32_e32 v108, v108
	v_log_f32_e32 v109, v109
	v_log_f32_e32 v110, v110
	v_log_f32_e32 v111, v111
	v_log_f32_e32 v112, v112
	v_log_f32_e32 v113, v113
	v_log_f32_e32 v114, v114
	v_log_f32_e32 v115, v115
	v_log_f32_e32 v116, v116
	v_log_f32_e32 v117, v117
	v_log_f32_e32 v118, v118
	v_log_f32_e32 v119, v119
	v_fmac_f32_e32 v120, 0xbf317218, v104
	v_fmac_f32_e32 v121, 0xbf317218, v105
	v_fmac_f32_e32 v122, 0xbf317218, v106
	v_fmac_f32_e32 v123, 0xbf317218, v107
	v_fmac_f32_e32 v124, 0xbf317218, v108
	v_fmac_f32_e32 v125, 0xbf317218, v109
	v_fmac_f32_e32 v126, 0xbf317218, v110
	v_fmac_f32_e32 v127, 0xbf317218, v111
	v_fmac_f32_e32 v128, 0xbf317218, v112
	v_fmac_f32_e32 v129, 0xbf317218, v113
	v_fmac_f32_e32 v130, 0xbf317218, v114
	v_fmac_f32_e32 v131, 0xbf317218, v115
	v_fmac_f32_e32 v132, 0xbf317218, v116
	v_fmac_f32_e32 v133, 0xbf317218, v117
	v_fmac_f32_e32 v134, 0xbf317218, v118
	v_fmac_f32_e32 v135, 0xbf317218, v119
	v_mul_f32_e32 v121, 0x3d800000, v121
	v_mul_f32_e32 v125, 0x3d800000, v125
	v_mul_f32_e32 v129, 0x3d800000, v129
	v_mul_f32_e32 v133, 0x3d800000, v133
	v_fmac_f32_e32 v121, 0x3d800000, v120
	v_fmac_f32_e32 v125, 0x3d800000, v124
	v_fmac_f32_e32 v129, 0x3d800000, v128
	v_fmac_f32_e32 v133, 0x3d800000, v132
	v_fmamk_f32 v122, v122, 0x3d800000, v121
	v_fmamk_f32 v126, v126, 0x3d800000, v125
	v_fmamk_f32 v130, v130, 0x3d800000, v129
	v_fmamk_f32 v134, v134, 0x3d800000, v133
	v_fmamk_f32 v123, v123, 0x3d800000, v122
	v_fmamk_f32 v127, v127, 0x3d800000, v126
	v_fmamk_f32 v131, v131, 0x3d800000, v130
	v_fmamk_f32 v135, v135, 0x3d800000, v134
	ds_bpermute_b32 v104, v173, v123
	ds_bpermute_b32 v105, v173, v127
	ds_bpermute_b32 v106, v173, v131
	ds_bpermute_b32 v107, v173, v135
	s_waitcnt lgkmcnt(0)
	v_cndmask_b32_e64 v104, v104, 0, s[4:5]
	v_cndmask_b32_e64 v105, v105, 0, s[4:5]
	v_cndmask_b32_e64 v106, v106, 0, s[4:5]
	v_cndmask_b32_e64 v107, v107, 0, s[4:5]
	v_add_f32_e32 v108, v104, v123
	v_add_f32_e32 v109, v105, v127
	v_add_f32_e32 v110, v106, v131
	v_add_f32_e32 v111, v107, v135
	ds_bpermute_b32 v104, v174, v108
	ds_bpermute_b32 v105, v174, v109
	ds_bpermute_b32 v106, v174, v110
	ds_bpermute_b32 v107, v174, v111
	s_waitcnt lgkmcnt(0)
	v_cndmask_b32_e64 v104, 0, v104, s[0:1]
	v_cndmask_b32_e64 v105, 0, v105, s[0:1]
	v_cndmask_b32_e64 v106, 0, v106, s[0:1]
	v_cndmask_b32_e64 v107, 0, v107, s[0:1]
	v_add_f32_e32 v108, v104, v108
	v_add_f32_e32 v109, v105, v109
	v_add_f32_e32 v110, v106, v110
	v_add_f32_e32 v111, v107, v111
	ds_bpermute_b32 v112, v175, v108
	ds_bpermute_b32 v113, v175, v109
	ds_bpermute_b32 v114, v175, v110
	ds_bpermute_b32 v115, v175, v111
	v_sub_f32_e32 v116, v108, v123
	v_sub_f32_e32 v117, v109, v127
	v_sub_f32_e32 v118, v110, v131
	v_sub_f32_e32 v119, v111, v135
	s_waitcnt lgkmcnt(0)
	v_add_f32_e32 v105, 0, v112
	v_add_f32_e32 v116, 0, v116
	v_add_f32_e32 v106, v105, v113
	v_add_f32_e32 v117, v105, v117
	v_add_f32_e32 v107, v106, v114
	v_add_f32_e32 v118, v106, v118
	v_add_f32_e32 v108, v107, v115
	v_add_f32_e32 v119, v107, v119
	v_fmamk_f32 v120, v120, 0x3d800000, v116
	v_fmamk_f32 v124, v124, 0x3d800000, v117
	v_fmamk_f32 v128, v128, 0x3d800000, v118
	v_fmamk_f32 v132, v132, 0x3d800000, v119
	v_add_f32_e32 v121, v121, v116
	v_add_f32_e32 v125, v125, v117
	v_add_f32_e32 v129, v129, v118
	v_add_f32_e32 v133, v133, v119
	v_add_f32_e32 v122, v122, v116
	v_add_f32_e32 v126, v126, v117
	v_add_f32_e32 v130, v130, v118
	v_add_f32_e32 v134, v134, v119
	v_add_f32_e32 v123, v123, v116
	v_add_f32_e32 v127, v127, v117
	v_add_f32_e32 v131, v131, v118
	v_add_f32_e32 v135, v135, v119
	ds_write_b32 v226, v120
	ds_write_b32 v226, v121 offset:528
	ds_write_b32 v226, v122 offset:1056
	ds_write_b32 v226, v123 offset:1584
	ds_write_b32 v226, v124 offset:8448
	ds_write_b32 v226, v125 offset:8976
	ds_write_b32 v226, v126 offset:9504
	ds_write_b32 v226, v127 offset:10032
	ds_write_b32 v226, v128 offset:16896
	ds_write_b32 v226, v129 offset:17424
	ds_write_b32 v226, v130 offset:17952
	ds_write_b32 v226, v131 offset:18480
	ds_write_b32 v226, v132 offset:25344
	ds_write_b32 v226, v133 offset:25872
	ds_write_b32 v226, v134 offset:26400
	ds_write_b32 v226, v135 offset:26928
	s_and_saveexec_b64 s[66:67], s[4:5]
	v_mul_f32_e32 v108, 0x3fb8aa3b, v108
	v_exp_f32_e32 v108, v108
	s_nop 0
	ds_write_b32 v176, v108
.LBB0_456:
	s_or_b64 exec, exec, s[66:67]
	s_cmp_lg_u32 s64, 0xe0000
	s_cselect_b64 s[28:29], -1, 0
	s_and_b64 s[28:29], vcc, s[28:29]
	s_waitcnt lgkmcnt(0)
	s_barrier
	s_and_saveexec_b64 s[66:67], s[28:29]
	s_cbranch_execz .LBB0_458
	s_waitcnt vmcnt(8)
	ds_write_b128 v177, v[242:245]

; __device__ __forceinline__ u32x4 pack8(const float (&f)[8]) { u32x4 w; w.x = cvt_pk_bf16(f[0], f[1]); w.y = cvt_pk_bf16(f[2], f[3]); w.z = cvt_pk_bf16(f[4], f[5]); w.w = cvt_pk_bf16(f[6], f[7]); return w; }
;     __device__ __forceinline__ void operator()(const f32x4 (&acc)[2][2][4][2], const Unit& u, int wr, int wc, int fr, int fq) const {
;         const int row0 = u.pm * BM + wr * 64 + fr, col0 = u.pn * BM + wc * 32 + 8 * fq;
; #pragma unroll
;         for (int ai = 0; ai < 2; ++ai)
; #pragma unroll
;             for (int m = 0; m < 4; ++m) { const int row = row0 + ai * HALF + m * 16; const size_t idx = (size_t)row * 1024 + col0; float ss = 0.f;
; #pragma unroll
;                 for (int bj = 0; bj < 2; ++bj) { const f32x4 x0 = __builtin_nontemporal_load((const f32x4*)(x + idx + bj * HALF)), x1 = __builtin_nontemporal_load((const f32x4*)(x + idx + bj * HALF + 4));
;                     const f32x4 h0 = x0 + acc[ai][bj][m][0], h1v = x1 + acc[ai][bj][m][1];
;                     float f[8] = {h0[0], h0[1], h0[2], h0[3], h1v[0], h1v[1], h1v[2], h1v[3]};
; #pragma unroll
;                     for (int e = 0; e < 8; ++e) ss += f[e] * f[e];
;                     *(u32x4*)(h1b + idx + bj * HALF) = pack8(f); }
.LBB0_648:
	v_lshl_add_u32 v148, s44, 8, v150
	v_lshl_or_b32 v146, s46, 8, v152
	v_lshl_add_u32 v144, v148, 10, v146
	v_lshlrev_b32_e32 v147, 2, v144
	v_lshlrev_b32_e32 v145, 1, v144
	v_lshlrev_b32_e32 v149, 2, v148
	global_load_dwordx4 v[158:161], v147, s[52:53] nt
	global_load_dwordx4 v[162:165], v147, s[52:53] offset:16 nt
	global_load_dwordx4 v[166:169], v147, s[52:53] offset:512 nt
	global_load_dwordx4 v[170:173], v147, s[52:53] offset:528 nt
	v_add_u32_e32 v147, 0x10000, v147
	global_load_dwordx4 v[174:177], v147, s[52:53] nt
	global_load_dwordx4 v[178:181], v147, s[52:53] offset:16 nt
	global_load_dwordx4 v[182:185], v147, s[52:53] offset:512 nt
	global_load_dwordx4 v[186:189], v147, s[52:53] offset:528 nt
	v_add_u32_e32 v147, 0x10000, v147
	global_load_dwordx4 v[190:193], v147, s[52:53] nt
	global_load_dwordx4 v[194:197], v147, s[52:53] offset:16 nt
	global_load_dwordx4 v[198:201], v147, s[52:53] offset:512 nt
	global_load_dwordx4 v[206:209], v147, s[52:53] offset:528 nt
	v_add_u32_e32 v147, 0x10000, v147
	global_load_dwordx4 v[210:213], v147, s[52:53] nt
	global_load_dwordx4 v[214:217], v147, s[52:53] offset:16 nt
	global_load_dwordx4 v[218:221], v147, s[52:53] offset:512 nt
	global_load_dwordx4 v[222:225], v147, s[52:53] offset:528 nt
	v_add_u32_e32 v147, 0x50000, v147
	global_load_dwordx4 v[226:229], v147, s[52:53] nt
	global_load_dwordx4 v[230:233], v147, s[52:53] offset:16 nt
	global_load_dwordx4 v[234:237], v147, s[52:53] offset:512 nt
	global_load_dwordx4 v[238:241], v147, s[52:53] offset:528 nt
	v_add_u32_e32 v147, 0x10000, v147
	s_waitcnt vmcnt(16)
	v_pk_add_f32 v[124:125], v[124:125], v[158:159]
	v_pk_add_f32 v[126:127], v[126:127], v[160:161]
	v_pk_add_f32 v[120:121], v[120:121], v[162:163]
	v_pk_add_f32 v[122:123], v[122:123], v[164:165]
	v_pk_add_f32 v[116:117], v[116:117], v[166:167]
	v_pk_add_f32 v[118:119], v[118:119], v[168:169]
	v_pk_add_f32 v[112:113], v[112:113], v[170:171]
	v_pk_add_f32 v[114:115], v[114:115], v[172:173]
	v_cvt_pk_bf16_f32 v158, v124, v125
	v_cvt_pk_bf16_f32 v159, v126, v127
	v_cvt_pk_bf16_f32 v160, v120, v121
	v_cvt_pk_bf16_f32 v161, v122, v123
	v_cvt_pk_bf16_f32 v166, v116, v117
	v_cvt_pk_bf16_f32 v167, v118, v119
	v_cvt_pk_bf16_f32 v168, v112, v113
	v_cvt_pk_bf16_f32 v169, v114, v115
	global_store_dwordx4 v145, v[158:161], s[8:9]
	global_store_dwordx4 v145, v[166:169], s[8:9] offset:256
	v_mul_f32_e32 v157, v124, v124
	v_fmac_f32_e32 v157, v125, v125
	v_fmac_f32_e32 v157, v126, v126
	v_fmac_f32_e32 v157, v127, v127
	v_fmac_f32_e32 v157, v120, v120
	v_fmac_f32_e32 v157, v121, v121
	v_fmac_f32_e32 v157, v122, v122
	v_fmac_f32_e32 v157, v123, v123
	v_fmac_f32_e32 v157, v116, v116
	v_fmac_f32_e32 v157, v117, v117
	v_fmac_f32_e32 v157, v118, v118
	v_fmac_f32_e32 v157, v119, v119
	v_fmac_f32_e32 v157, v112, v112
	v_fmac_f32_e32 v157, v113, v113
	v_fmac_f32_e32 v157, v114, v114
	v_fmac_f32_e32 v157, v115, v115
	v_add_u32_e32 v145, 0x8000, v145
	global_load_dwordx4 v[158:161], v147, s[52:53] nt
	global_load_dwordx4 v[162:165], v147, s[52:53] offset:16 nt
	global_load_dwordx4 v[166:169], v147, s[52:53] offset:512 nt
	global_load_dwordx4 v[170:173], v147, s[52:53] offset:528 nt
	v_add_u32_e32 v147, 0x10000, v147
	s_waitcnt vmcnt(18)
	v_pk_add_f32 v[108:109], v[108:109], v[174:175]
	v_pk_add_f32 v[110:111], v[110:111], v[176:177]
	v_pk_add_f32 v[104:105], v[104:105], v[178:179]
	v_pk_add_f32 v[106:107], v[106:107], v[180:181]
	v_pk_add_f32 v[100:101], v[100:101], v[182:183]
	v_pk_add_f32 v[102:103], v[102:103], v[184:185]
	v_pk_add_f32 v[96:97], v[96:97], v[186:187]
	v_pk_add_f32 v[98:99], v[98:99], v[188:189]
	v_cvt_pk_bf16_f32 v174, v108, v109
	v_cvt_pk_bf16_f32 v175, v110, v111
	v_cvt_pk_bf16_f32 v176, v104, v105
	v_cvt_pk_bf16_f32 v177, v106, v107
	v_cvt_pk_bf16_f32 v182, v100, v101
	v_cvt_pk_bf16_f32 v183, v102, v103
	v_cvt_pk_bf16_f32 v184, v96, v97
	v_cvt_pk_bf16_f32 v185, v98, v99
	global_store_dwordx4 v145, v[174:177], s[8:9]
	global_store_dwordx4 v145, v[182:185], s[8:9] offset:256
	v_mul_f32_e32 v202, v108, v108
	v_fmac_f32_e32 v202, v109, v109
	v_fmac_f32_e32 v202, v110, v110
	v_fmac_f32_e32 v202, v111, v111
	v_fmac_f32_e32 v202, v104, v104
	v_fmac_f32_e32 v202, v105, v105
	v_fmac_f32_e32 v202, v106, v106
	v_fmac_f32_e32 v202, v107, v107
	v_fmac_f32_e32 v202, v100, v100
	v_fmac_f32_e32 v202, v101, v101
	v_fmac_f32_e32 v202, v102, v102
	v_fmac_f32_e32 v202, v103, v103
	v_fmac_f32_e32 v202, v96, v96
	v_fmac_f32_e32 v202, v97, v97
	v_fmac_f32_e32 v202, v98, v98
	v_fmac_f32_e32 v202, v99, v99
	v_add_u32_e32 v145, 0x8000, v145
	global_load_dwordx4 v[174:177], v147, s[52:53] nt
	global_load_dwordx4 v[178:181], v147, s[52:53] offset:16 nt
	global_load_dwordx4 v[182:185], v147, s[52:53] offset:512 nt
	global_load_dwordx4 v[186:189], v147, s[52:53] offset:528 nt
	v_add_u32_e32 v147, 0x10000, v147
	s_waitcnt vmcnt(20)
	v_pk_add_f32 v[92:93], v[92:93], v[190:191]
	v_pk_add_f32 v[94:95], v[94:95], v[192:193]
	v_pk_add_f32 v[88:89], v[88:89], v[194:195]
	v_pk_add_f32 v[90:91], v[90:91], v[196:197]
	v_pk_add_f32 v[84:85], v[84:85], v[198:199]
	v_pk_add_f32 v[86:87], v[86:87], v[200:201]
	v_pk_add_f32 v[80:81], v[80:81], v[206:207]
	v_pk_add_f32 v[82:83], v[82:83], v[208:209]
	v_cvt_pk_bf16_f32 v190, v92, v93
	v_cvt_pk_bf16_f32 v191, v94, v95
	v_cvt_pk_bf16_f32 v192, v88, v89
	v_cvt_pk_bf16_f32 v193, v90, v91
	v_cvt_pk_bf16_f32 v198, v84, v85
	v_cvt_pk_bf16_f32 v199, v86, v87
	v_cvt_pk_bf16_f32 v200, v80, v81
	v_cvt_pk_bf16_f32 v201, v82, v83
	global_store_dwordx4 v145, v[190:193], s[8:9]
	global_store_dwordx4 v145, v[198:201], s[8:9] offset:256
	v_mul_f32_e32 v203, v92, v92
	v_fmac_f32_e32 v203, v93, v93
	v_fmac_f32_e32 v203, v94, v94
	v_fmac_f32_e32 v203, v95, v95
	v_fmac_f32_e32 v203, v88, v88
	v_fmac_f32_e32 v203, v89, v89
	v_fmac_f32_e32 v203, v90, v90
	v_fmac_f32_e32 v203, v91, v91
	v_fmac_f32_e32 v203, v84, v84
	v_fmac_f32_e32 v203, v85, v85
	v_fmac_f32_e32 v203, v86, v86
	v_fmac_f32_e32 v203, v87, v87
	v_fmac_f32_e32 v203, v80, v80
	v_fmac_f32_e32 v203, v81, v81
	v_fmac_f32_e32 v203, v82, v82
	v_fmac_f32_e32 v203, v83, v83
	v_add_u32_e32 v145, 0x8000, v145
	global_load_dwordx4 v[190:193], v147, s[52:53] nt
	global_load_dwordx4 v[194:197], v147, s[52:53] offset:16 nt
	global_load_dwordx4 v[198:201], v147, s[52:53] offset:512 nt
	global_load_dwordx4 v[206:209], v147, s[52:53] offset:528 nt
	s_waitcnt vmcnt(22)
; __device__ __forceinline__ u32x4 pack8(const float (&f)[8]) { u32x4 w; w.x = cvt_pk_bf16(f[0], f[1]); w.y = cvt_pk_bf16(f[2], f[3]); w.z = cvt_pk_bf16(f[4], f[5]); w.w = cvt_pk_bf16(f[6], f[7]); return w; }
;     __device__ __forceinline__ void operator()(const f32x4 (&acc)[2][2][4][2], const Unit& u, int wr, int wc, int fr, int fq) const {
;     ...
;             for (int m = 0; m < 4; ++m) { const int row = row0 + ai * HALF + m * 16; const size_t idx = (size_t)row * 1024 + col0; float ss = 0.f;
; #pragma unroll
;                 for (int bj = 0; bj < 2; ++bj) { const f32x4 x0 = __builtin_nontemporal_load((const f32x4*)(x + idx + bj * HALF)), x1 = __builtin_nontemporal_load((const f32x4*)(x + idx + bj * HALF + 4));
;                     const f32x4 h0 = x0 + acc[ai][bj][m][0], h1v = x1 + acc[ai][bj][m][1];
;                     float f[8] = {h0[0], h0[1], h0[2], h0[3], h1v[0], h1v[1], h1v[2], h1v[3]};
; #pragma unroll
;                     for (int e = 0; e < 8; ++e) ss += f[e] * f[e];
;                     *(u32x4*)(h1b + idx + bj * HALF) = pack8(f); }
	v_pk_add_f32 v[76:77], v[76:77], v[210:211]
	v_pk_add_f32 v[78:79], v[78:79], v[212:213]
	v_pk_add_f32 v[72:73], v[72:73], v[214:215]
	v_pk_add_f32 v[74:75], v[74:75], v[216:217]
	v_pk_add_f32 v[68:69], v[68:69], v[218:219]
	v_pk_add_f32 v[70:71], v[70:71], v[220:221]
	v_pk_add_f32 v[64:65], v[64:65], v[222:223]
	v_pk_add_f32 v[66:67], v[66:67], v[224:225]
	v_cvt_pk_bf16_f32 v210, v76, v77
	v_cvt_pk_bf16_f32 v211, v78, v79
	v_cvt_pk_bf16_f32 v212, v72, v73
	v_cvt_pk_bf16_f32 v213, v74, v75
	v_cvt_pk_bf16_f32 v218, v68, v69
	v_cvt_pk_bf16_f32 v219, v70, v71
	v_cvt_pk_bf16_f32 v220, v64, v65
	v_cvt_pk_bf16_f32 v221, v66, v67
	global_store_dwordx4 v145, v[210:213], s[8:9]
	global_store_dwordx4 v145, v[218:221], s[8:9] offset:256
	v_mul_f32_e32 v205, v76, v76
	v_fmac_f32_e32 v205, v77, v77
	v_fmac_f32_e32 v205, v78, v78
	v_fmac_f32_e32 v205, v79, v79
	v_fmac_f32_e32 v205, v72, v72
	v_fmac_f32_e32 v205, v73, v73
	v_fmac_f32_e32 v205, v74, v74
	v_fmac_f32_e32 v205, v75, v75
	v_fmac_f32_e32 v205, v68, v68
	v_fmac_f32_e32 v205, v69, v69
	v_fmac_f32_e32 v205, v70, v70
	v_fmac_f32_e32 v205, v71, v71
	v_fmac_f32_e32 v205, v64, v64
	v_fmac_f32_e32 v205, v65, v65
	v_fmac_f32_e32 v205, v66, v66
	v_fmac_f32_e32 v205, v67, v67
	v_add_u32_e32 v145, 0x28000, v145
	s_waitcnt vmcnt(20)
	v_pk_add_f32 v[60:61], v[60:61], v[226:227]
	v_pk_add_f32 v[62:63], v[62:63], v[228:229]
	v_pk_add_f32 v[56:57], v[56:57], v[230:231]
	v_pk_add_f32 v[58:59], v[58:59], v[232:233]
	v_pk_add_f32 v[52:53], v[52:53], v[234:235]
	v_pk_add_f32 v[54:55], v[54:55], v[236:237]
	v_pk_add_f32 v[48:49], v[48:49], v[238:239]
	v_pk_add_f32 v[50:51], v[50:51], v[240:241]
	v_cvt_pk_bf16_f32 v226, v60, v61
	v_cvt_pk_bf16_f32 v227, v62, v63
	v_cvt_pk_bf16_f32 v228, v56, v57
	v_cvt_pk_bf16_f32 v229, v58, v59
	v_cvt_pk_bf16_f32 v234, v52, v53
	v_cvt_pk_bf16_f32 v235, v54, v55
	v_cvt_pk_bf16_f32 v236, v48, v49
	v_cvt_pk_bf16_f32 v237, v50, v51
	global_store_dwordx4 v145, v[226:229], s[8:9]
	global_store_dwordx4 v145, v[234:237], s[8:9] offset:256
	v_mul_f32_e32 v242, v60, v60
	v_fmac_f32_e32 v242, v61, v61
	v_fmac_f32_e32 v242, v62, v62
	v_fmac_f32_e32 v242, v63, v63
	v_fmac_f32_e32 v242, v56, v56
	v_fmac_f32_e32 v242, v57, v57
	v_fmac_f32_e32 v242, v58, v58
	v_fmac_f32_e32 v242, v59, v59
	v_fmac_f32_e32 v242, v52, v52
	v_fmac_f32_e32 v242, v53, v53
	v_fmac_f32_e32 v242, v54, v54
	v_fmac_f32_e32 v242, v55, v55
	v_fmac_f32_e32 v242, v48, v48
	v_fmac_f32_e32 v242, v49, v49
	v_fmac_f32_e32 v242, v50, v50
	v_fmac_f32_e32 v242, v51, v51
	v_add_u32_e32 v145, 0x8000, v145
	s_waitcnt vmcnt(16)
	v_pk_add_f32 v[44:45], v[44:45], v[158:159]
	v_pk_add_f32 v[46:47], v[46:47], v[160:161]
	v_pk_add_f32 v[40:41], v[40:41], v[162:163]
	v_pk_add_f32 v[42:43], v[42:43], v[164:165]
	v_pk_add_f32 v[36:37], v[36:37], v[166:167]
	v_pk_add_f32 v[38:39], v[38:39], v[168:169]
	v_pk_add_f32 v[32:33], v[32:33], v[170:171]
	v_pk_add_f32 v[34:35], v[34:35], v[172:173]
	v_cvt_pk_bf16_f32 v158, v44, v45
	v_cvt_pk_bf16_f32 v159, v46, v47
	v_cvt_pk_bf16_f32 v160, v40, v41
	v_cvt_pk_bf16_f32 v161, v42, v43
	v_cvt_pk_bf16_f32 v166, v36, v37
	v_cvt_pk_bf16_f32 v167, v38, v39
	v_cvt_pk_bf16_f32 v168, v32, v33
	v_cvt_pk_bf16_f32 v169, v34, v35
	global_store_dwordx4 v145, v[158:161], s[8:9]
	global_store_dwordx4 v145, v[166:169], s[8:9] offset:256
	v_mul_f32_e32 v243, v44, v44
	v_fmac_f32_e32 v243, v45, v45
	v_fmac_f32_e32 v243, v46, v46
	v_fmac_f32_e32 v243, v47, v47
	v_fmac_f32_e32 v243, v40, v40
	v_fmac_f32_e32 v243, v41, v41
	v_fmac_f32_e32 v243, v42, v42
	v_fmac_f32_e32 v243, v43, v43
	v_fmac_f32_e32 v243, v36, v36
	v_fmac_f32_e32 v243, v37, v37
	v_fmac_f32_e32 v243, v38, v38
	v_fmac_f32_e32 v243, v39, v39
	v_fmac_f32_e32 v243, v32, v32
	v_fmac_f32_e32 v243, v33, v33
	v_fmac_f32_e32 v243, v34, v34
	v_fmac_f32_e32 v243, v35, v35
	v_add_u32_e32 v145, 0x8000, v145
	s_waitcnt vmcnt(12)
; __device__ __forceinline__ u32x4 pack8(const float (&f)[8]) { u32x4 w; w.x = cvt_pk_bf16(f[0], f[1]); w.y = cvt_pk_bf16(f[2], f[3]); w.z = cvt_pk_bf16(f[4], f[5]); w.w = cvt_pk_bf16(f[6], f[7]); return w; }
;     __device__ __forceinline__ void operator()(const f32x4 (&acc)[2][2][4][2], const Unit& u, int wr, int wc, int fr, int fq) const {
;     ...
;             for (int m = 0; m < 4; ++m) { const int row = row0 + ai * HALF + m * 16; const size_t idx = (size_t)row * 1024 + col0; float ss = 0.f;
; #pragma unroll
;                 for (int bj = 0; bj < 2; ++bj) { const f32x4 x0 = __builtin_nontemporal_load((const f32x4*)(x + idx + bj * HALF)), x1 = __builtin_nontemporal_load((const f32x4*)(x + idx + bj * HALF + 4));
;                     const f32x4 h0 = x0 + acc[ai][bj][m][0], h1v = x1 + acc[ai][bj][m][1];
;                     float f[8] = {h0[0], h0[1], h0[2], h0[3], h1v[0], h1v[1], h1v[2], h1v[3]};
; #pragma unroll
;                     for (int e = 0; e < 8; ++e) ss += f[e] * f[e];
;                     *(u32x4*)(h1b + idx + bj * HALF) = pack8(f); }
;                 ss += __shfl_xor(ss, 16); ss += __shfl_xor(ss, 32);
;                 if (fq == 0) atomicAdd(ssq + row, ss); }
	v_pk_add_f32 v[28:29], v[28:29], v[174:175]
	v_pk_add_f32 v[30:31], v[30:31], v[176:177]
	v_pk_add_f32 v[24:25], v[24:25], v[178:179]
	v_pk_add_f32 v[26:27], v[26:27], v[180:181]
	v_pk_add_f32 v[20:21], v[20:21], v[182:183]
	v_pk_add_f32 v[22:23], v[22:23], v[184:185]
	v_pk_add_f32 v[16:17], v[16:17], v[186:187]
	v_pk_add_f32 v[18:19], v[18:19], v[188:189]
	v_cvt_pk_bf16_f32 v174, v28, v29
	v_cvt_pk_bf16_f32 v175, v30, v31
	v_cvt_pk_bf16_f32 v176, v24, v25
	v_cvt_pk_bf16_f32 v177, v26, v27
	v_cvt_pk_bf16_f32 v182, v20, v21
	v_cvt_pk_bf16_f32 v183, v22, v23
	v_cvt_pk_bf16_f32 v184, v16, v17
	v_cvt_pk_bf16_f32 v185, v18, v19
	global_store_dwordx4 v145, v[174:177], s[8:9]
	global_store_dwordx4 v145, v[182:185], s[8:9] offset:256
	v_mul_f32_e32 v244, v28, v28
	v_fmac_f32_e32 v244, v29, v29
	v_fmac_f32_e32 v244, v30, v30
	v_fmac_f32_e32 v244, v31, v31
	v_fmac_f32_e32 v244, v24, v24
	v_fmac_f32_e32 v244, v25, v25
	v_fmac_f32_e32 v244, v26, v26
	v_fmac_f32_e32 v244, v27, v27
	v_fmac_f32_e32 v244, v20, v20
	v_fmac_f32_e32 v244, v21, v21
	v_fmac_f32_e32 v244, v22, v22
	v_fmac_f32_e32 v244, v23, v23
	v_fmac_f32_e32 v244, v16, v16
	v_fmac_f32_e32 v244, v17, v17
	v_fmac_f32_e32 v244, v18, v18
	v_fmac_f32_e32 v244, v19, v19
	v_add_u32_e32 v145, 0x8000, v145
	s_waitcnt vmcnt(8)
	v_pk_add_f32 v[12:13], v[12:13], v[190:191]
	v_pk_add_f32 v[14:15], v[14:15], v[192:193]
	v_pk_add_f32 v[8:9], v[8:9], v[194:195]
	v_pk_add_f32 v[10:11], v[10:11], v[196:197]
	v_pk_add_f32 v[4:5], v[4:5], v[198:199]
	v_pk_add_f32 v[6:7], v[6:7], v[200:201]
	v_pk_add_f32 v[0:1], v[0:1], v[206:207]
	v_pk_add_f32 v[2:3], v[2:3], v[208:209]
	v_cvt_pk_bf16_f32 v190, v12, v13
	v_cvt_pk_bf16_f32 v191, v14, v15
	v_cvt_pk_bf16_f32 v192, v8, v9
	v_cvt_pk_bf16_f32 v193, v10, v11
	v_cvt_pk_bf16_f32 v198, v4, v5
	v_cvt_pk_bf16_f32 v199, v6, v7
	v_cvt_pk_bf16_f32 v200, v0, v1
	v_cvt_pk_bf16_f32 v201, v2, v3
	global_store_dwordx4 v145, v[190:193], s[8:9]
	global_store_dwordx4 v145, v[198:201], s[8:9] offset:256
	v_mul_f32_e32 v245, v12, v12
	v_fmac_f32_e32 v245, v13, v13
	v_fmac_f32_e32 v245, v14, v14
	v_fmac_f32_e32 v245, v15, v15
	v_fmac_f32_e32 v245, v8, v8
	v_fmac_f32_e32 v245, v9, v9
	v_fmac_f32_e32 v245, v10, v10
	v_fmac_f32_e32 v245, v11, v11
	v_fmac_f32_e32 v245, v4, v4
	v_fmac_f32_e32 v245, v5, v5
	v_fmac_f32_e32 v245, v6, v6
	v_fmac_f32_e32 v245, v7, v7
	v_fmac_f32_e32 v245, v0, v0
	v_fmac_f32_e32 v245, v1, v1
	v_fmac_f32_e32 v245, v2, v2
	v_fmac_f32_e32 v245, v3, v3
	v_xor_b32_e32 v158, 16, v156
	v_xor_b32_e32 v159, 32, v156
	v_lshlrev_b32_e32 v158, 2, v158
	v_lshlrev_b32_e32 v159, 2, v159
	ds_bpermute_b32 v162, v158, v157
	ds_bpermute_b32 v163, v158, v202
	ds_bpermute_b32 v164, v158, v203
	ds_bpermute_b32 v165, v158, v205
	ds_bpermute_b32 v166, v158, v242
	ds_bpermute_b32 v167, v158, v243
	ds_bpermute_b32 v168, v158, v244
	ds_bpermute_b32 v169, v158, v245
	s_waitcnt lgkmcnt(0)
	v_add_f32_e32 v157, v157, v162
	v_add_f32_e32 v202, v202, v163
	v_add_f32_e32 v203, v203, v164
	v_add_f32_e32 v205, v205, v165
	v_add_f32_e32 v242, v242, v166
	v_add_f32_e32 v243, v243, v167
	v_add_f32_e32 v244, v244, v168
	v_add_f32_e32 v245, v245, v169
	ds_bpermute_b32 v162, v159, v157
	ds_bpermute_b32 v163, v159, v202
	ds_bpermute_b32 v164, v159, v203
	ds_bpermute_b32 v165, v159, v205
	ds_bpermute_b32 v166, v159, v242
	ds_bpermute_b32 v167, v159, v243
	ds_bpermute_b32 v168, v159, v244
	ds_bpermute_b32 v169, v159, v245
	s_waitcnt lgkmcnt(0)
	v_add_f32_e32 v157, v157, v162
	v_add_f32_e32 v202, v202, v163
	v_add_f32_e32 v203, v203, v164
	v_add_f32_e32 v205, v205, v165
	v_add_f32_e32 v242, v242, v166
	v_add_f32_e32 v243, v243, v167
	v_add_f32_e32 v244, v244, v168
	v_add_f32_e32 v245, v245, v169
	s_and_saveexec_b64 s[44:45], s[4:5]
	global_atomic_add_f32 v149, v157, s[68:69]
	global_atomic_add_f32 v149, v202, s[68:69] offset:64
	global_atomic_add_f32 v149, v203, s[68:69] offset:128
	global_atomic_add_f32 v149, v205, s[68:69] offset:192
	global_atomic_add_f32 v149, v242, s[68:69] offset:512
	global_atomic_add_f32 v149, v243, s[68:69] offset:576
	global_atomic_add_f32 v149, v244, s[68:69] offset:640
	global_atomic_add_f32 v149, v245, s[68:69] offset:704
	s_or_b64 exec, exec, s[44:45]
	s_andn2_b64 vcc, exec, s[6:7]
	s_mov_b64 s[6:7], -1
	s_cbranch_vccnz .LBB0_637
	s_andn2_b64 vcc, exec, s[12:13]
	s_cbranch_vccnz .LBB0_636
	s_barrier
	s_branch .LBB0_636
